# local attention tiles: rpb bias LDS reads batched (unconditional reads into free VGPRs, one wait, cndmask) instead of 16 predicated read+wait blocks
# baseline (speedup 1.0000x reference)
.LBB0_849:
	s_cmp_gt_u32 s62, 15
	s_mov_b64 s[10:11], -1
	s_cbranch_scc0 .LBB0_979
	s_sub_i32 s10, s20, 20
	s_lshr_b32 s10, s10, 1
	s_and_b32 s11, s62, 1
	s_add_i32 s10, s10, s60
	v_lshl_or_b32 v0, s11, 5, v198
	s_mulk_i32 s10, 0x7c
	s_add_i32 s10, s15, s10
	v_sub_u32_e32 v1, v0, v193
	v_lshl_add_u32 v5, v1, 2, s10
	s_cmp_lg_u32 s11, s47
	v_sub_u32_e32 v6, v0, v223
	s_mov_b64 s[10:11], -1
	s_cbranch_scc0 .LBB0_875
	s_and_b64 vcc, exec, s[6:7]
	s_cbranch_vccz .LBB0_863
	s_waitcnt vmcnt(7)
	v_mfma_f32_32x32x16_bf16 v[48:63], v[96:99], v[80:83], 0
	v_add_u32_e32 v0, 24, v6
	v_cmp_gt_u32_e32 vcc, 16, v0
	v_mov_b32_e32 v0, 0xf149f2ca
	v_mov_b32_e32 v1, 0xf149f2ca
	s_waitcnt vmcnt(6)
	v_mfma_f32_32x32x16_bf16 v[48:63], v[100:103], v[84:87], v[48:63]
	s_waitcnt vmcnt(3)
	v_mfma_f32_32x32x16_bf16 v[48:63], v[112:115], v[88:91], v[48:63]
	s_waitcnt vmcnt(2)
	v_mfma_f32_32x32x16_bf16 v[48:63], v[116:119], v[92:95], v[48:63]
	ds_read_b32 v233, v5 offset:2048
	ds_read_b32 v234, v5 offset:2052
	ds_read_b32 v235, v5 offset:2056
	ds_read_b32 v236, v5 offset:2060
	s_waitcnt lgkmcnt(0)
	s_nop 7
	v_fmac_f32_e32 v233, 0x3e38aa3b, v60
	s_nop 0
	v_cndmask_b32_e32 v1, v1, v233, vcc
	v_add_u32_e32 v3, 25, v6
	v_cmp_gt_u32_e32 vcc, 16, v3
	v_fmac_f32_e32 v234, 0x3e38aa3b, v61
	s_nop 0
	v_cndmask_b32_e32 v0, v0, v234, vcc
	v_add_u32_e32 v3, 26, v6
	v_cmp_gt_u32_e32 vcc, 16, v3
	v_mov_b32_e32 v3, 0xf149f2ca
	v_mov_b32_e32 v7, 0xf149f2ca
	v_fmac_f32_e32 v235, 0x3e38aa3b, v62
	s_nop 0
	v_cndmask_b32_e32 v7, v7, v235, vcc
	v_add_u32_e32 v8, 27, v6
	v_cmp_gt_u32_e32 vcc, 16, v8
	v_fmac_f32_e32 v236, 0x3e38aa3b, v63
	s_nop 0
	v_cndmask_b32_e32 v3, v3, v236, vcc
	v_max_f32_e32 v8, v0, v0
	v_max_f32_e32 v9, v1, v1
	v_max_f32_e32 v8, v9, v8
	v_max3_f32 v9, v8, v7, v3
	ds_bpermute_b32 v10, v224, v9
	v_mov_b64_e32 v[78:79], v[46:47]
	v_mov_b64_e32 v[62:63], v[30:31]
	v_mov_b32_e32 v8, v201
	v_mov_b32_e32 v205, v4
	s_waitcnt lgkmcnt(0)
	v_max3_f32 v9, v4, v9, v10
	v_mov_b64_e32 v[76:77], v[44:45]
	v_mov_b64_e32 v[74:75], v[42:43]
	v_mov_b64_e32 v[72:73], v[40:41]
	v_mov_b64_e32 v[70:71], v[38:39]
	v_mov_b64_e32 v[68:69], v[36:37]
	v_mov_b64_e32 v[66:67], v[34:35]
	v_mov_b64_e32 v[64:65], v[32:33]
	v_cmp_gt_f32_e32 vcc, v9, v4
	v_mov_b64_e32 v[60:61], v[28:29]
	v_mov_b64_e32 v[58:59], v[26:27]
	v_mov_b64_e32 v[56:57], v[24:25]
	v_mov_b64_e32 v[54:55], v[22:23]
	v_mov_b64_e32 v[52:53], v[20:21]
	v_mov_b64_e32 v[50:51], v[18:19]
	v_mov_b64_e32 v[48:49], v[16:17]
	s_cbranch_vccz .LBB0_862
	v_sub_f32_e32 v8, v4, v9
	v_exp_f32_e32 v10, v8
	v_mov_b32_e32 v205, v9
	v_mul_f32_e32 v8, v201, v10
	v_pk_mul_f32 v[62:63], v[30:31], v[10:11] op_sel_hi:[1,0]
	v_pk_mul_f32 v[60:61], v[28:29], v[10:11] op_sel_hi:[1,0]
	v_pk_mul_f32 v[58:59], v[26:27], v[10:11] op_sel_hi:[1,0]
	v_pk_mul_f32 v[56:57], v[24:25], v[10:11] op_sel_hi:[1,0]
	v_pk_mul_f32 v[54:55], v[22:23], v[10:11] op_sel_hi:[1,0]
	v_pk_mul_f32 v[52:53], v[20:21], v[10:11] op_sel_hi:[1,0]
	v_pk_mul_f32 v[50:51], v[18:19], v[10:11] op_sel_hi:[1,0]
	v_pk_mul_f32 v[48:49], v[16:17], v[10:11] op_sel_hi:[1,0]
	v_pk_mul_f32 v[78:79], v[46:47], v[10:11] op_sel_hi:[1,0]
	v_pk_mul_f32 v[76:77], v[44:45], v[10:11] op_sel_hi:[1,0]
	v_pk_mul_f32 v[74:75], v[42:43], v[10:11] op_sel_hi:[1,0]
	v_pk_mul_f32 v[72:73], v[40:41], v[10:11] op_sel_hi:[1,0]
	v_pk_mul_f32 v[70:71], v[38:39], v[10:11] op_sel_hi:[1,0]
	v_pk_mul_f32 v[68:69], v[36:37], v[10:11] op_sel_hi:[1,0]
	v_pk_mul_f32 v[66:67], v[34:35], v[10:11] op_sel_hi:[1,0]
	v_pk_mul_f32 v[64:65], v[32:33], v[10:11] op_sel_hi:[1,0]

.LBB0_863:
	s_and_b64 vcc, exec, s[10:11]
	s_cbranch_vccz .LBB0_1054
	s_waitcnt vmcnt(7)
	v_mfma_f32_32x32x16_bf16 v[48:63], v[96:99], v[80:83], 0
	v_cmp_gt_u32_e32 vcc, 16, v6
	v_mov_b32_e32 v1, 0xf149f2ca
	v_mov_b32_e32 v0, 0xf149f2ca
	s_waitcnt vmcnt(6)
	v_mfma_f32_32x32x16_bf16 v[48:63], v[100:103], v[84:87], v[48:63]
	s_waitcnt vmcnt(3)
	v_mfma_f32_32x32x16_bf16 v[48:63], v[112:115], v[88:91], v[48:63]
	s_waitcnt vmcnt(2)
	v_mfma_f32_32x32x16_bf16 v[48:63], v[116:119], v[92:95], v[48:63]
	ds_read_b32 v233, v5 offset:1952
	ds_read_b32 v234, v5 offset:1956
	ds_read_b32 v235, v5 offset:1960
	ds_read_b32 v236, v5 offset:1964
	s_waitcnt lgkmcnt(0)
	s_nop 7
	v_fmac_f32_e32 v233, 0x3e38aa3b, v48
	s_nop 0
	v_cndmask_b32_e32 v0, v0, v233, vcc
	v_add_u32_e32 v3, 1, v6
	v_cmp_gt_u32_e32 vcc, 16, v3
	v_fmac_f32_e32 v234, 0x3e38aa3b, v49
	s_nop 0
	v_cndmask_b32_e32 v1, v1, v234, vcc
	v_add_u32_e32 v3, 2, v6
	v_cmp_gt_u32_e32 vcc, 16, v3
	v_mov_b32_e32 v7, 0xf149f2ca
	v_mov_b32_e32 v3, 0xf149f2ca
	v_fmac_f32_e32 v235, 0x3e38aa3b, v50
	s_nop 0
	v_cndmask_b32_e32 v3, v3, v235, vcc
	v_add_u32_e32 v8, 3, v6
	v_cmp_gt_u32_e32 vcc, 16, v8
	v_fmac_f32_e32 v236, 0x3e38aa3b, v51
	s_nop 0
	v_cndmask_b32_e32 v7, v7, v236, vcc
	v_max_f32_e32 v8, v1, v1
	v_max_f32_e32 v9, v0, v0
	v_max_f32_e32 v8, v9, v8
	v_max3_f32 v9, v8, v3, v7
	ds_bpermute_b32 v10, v224, v9
	v_mov_b64_e32 v[78:79], v[46:47]
	v_mov_b64_e32 v[62:63], v[30:31]
	v_mov_b32_e32 v8, v201
	v_mov_b32_e32 v205, v4
	s_waitcnt lgkmcnt(0)
	v_max3_f32 v9, v4, v9, v10
	v_mov_b64_e32 v[76:77], v[44:45]
	v_mov_b64_e32 v[74:75], v[42:43]
	v_mov_b64_e32 v[72:73], v[40:41]
	v_mov_b64_e32 v[70:71], v[38:39]
	v_mov_b64_e32 v[68:69], v[36:37]
	v_mov_b64_e32 v[66:67], v[34:35]
	v_mov_b64_e32 v[64:65], v[32:33]
	v_cmp_gt_f32_e32 vcc, v9, v4
	v_mov_b64_e32 v[60:61], v[28:29]
	v_mov_b64_e32 v[58:59], v[26:27]
	v_mov_b64_e32 v[56:57], v[24:25]
	v_mov_b64_e32 v[54:55], v[22:23]
	v_mov_b64_e32 v[52:53], v[20:21]
	v_mov_b64_e32 v[50:51], v[18:19]
	v_mov_b64_e32 v[48:49], v[16:17]
	s_cbranch_vccz .LBB0_874
	v_sub_f32_e32 v8, v4, v9
	v_exp_f32_e32 v10, v8
	v_mov_b32_e32 v205, v9
	v_mul_f32_e32 v8, v201, v10
	v_pk_mul_f32 v[62:63], v[30:31], v[10:11] op_sel_hi:[1,0]
	v_pk_mul_f32 v[60:61], v[28:29], v[10:11] op_sel_hi:[1,0]
	v_pk_mul_f32 v[58:59], v[26:27], v[10:11] op_sel_hi:[1,0]
	v_pk_mul_f32 v[56:57], v[24:25], v[10:11] op_sel_hi:[1,0]
	v_pk_mul_f32 v[54:55], v[22:23], v[10:11] op_sel_hi:[1,0]
	v_pk_mul_f32 v[52:53], v[20:21], v[10:11] op_sel_hi:[1,0]
	v_pk_mul_f32 v[50:51], v[18:19], v[10:11] op_sel_hi:[1,0]
	v_pk_mul_f32 v[48:49], v[16:17], v[10:11] op_sel_hi:[1,0]
	v_pk_mul_f32 v[78:79], v[46:47], v[10:11] op_sel_hi:[1,0]
	v_pk_mul_f32 v[76:77], v[44:45], v[10:11] op_sel_hi:[1,0]
	v_pk_mul_f32 v[74:75], v[42:43], v[10:11] op_sel_hi:[1,0]
	v_pk_mul_f32 v[72:73], v[40:41], v[10:11] op_sel_hi:[1,0]
	v_pk_mul_f32 v[70:71], v[38:39], v[10:11] op_sel_hi:[1,0]
	v_pk_mul_f32 v[68:69], v[36:37], v[10:11] op_sel_hi:[1,0]
	v_pk_mul_f32 v[66:67], v[34:35], v[10:11] op_sel_hi:[1,0]
	v_pk_mul_f32 v[64:65], v[32:33], v[10:11] op_sel_hi:[1,0]

.LBB0_876:
	s_waitcnt vmcnt(7)
	v_mfma_f32_32x32x16_bf16 v[48:63], v[96:99], v[80:83], 0
	v_cmp_gt_u32_e32 vcc, 16, v6
	v_mov_b32_e32 v0, 0xf149f2ca
	v_mov_b32_e32 v1, 0xf149f2ca
	s_waitcnt vmcnt(6)
	v_mfma_f32_32x32x16_bf16 v[48:63], v[100:103], v[84:87], v[48:63]
	s_waitcnt vmcnt(3)
	v_mfma_f32_32x32x16_bf16 v[48:63], v[112:115], v[88:91], v[48:63]
	s_waitcnt vmcnt(2)
	v_mfma_f32_32x32x16_bf16 v[48:63], v[116:119], v[92:95], v[48:63]
	ds_read_b32 v233, v5 offset:1952
	ds_read_b32 v234, v5 offset:1956
	ds_read_b32 v235, v5 offset:1960
	ds_read_b32 v236, v5 offset:1964
	ds_read_b32 v237, v5 offset:1984
	ds_read_b32 v238, v5 offset:1988
	ds_read_b32 v239, v5 offset:1992
	ds_read_b32 v240, v5 offset:1996
	ds_read_b32 v241, v5 offset:2016
	ds_read_b32 v242, v5 offset:2020
	ds_read_b32 v243, v5 offset:2024
	ds_read_b32 v244, v5 offset:2028
	ds_read_b32 v245, v5 offset:2048
	ds_read_b32 v246, v5 offset:2052
	ds_read_b32 v247, v5 offset:2056
	ds_read_b32 v248, v5 offset:2060
	s_waitcnt lgkmcnt(0)
	v_fmac_f32_e32 v233, 0x3e38aa3b, v48
	s_nop 0
	v_cndmask_b32_e32 v1, v1, v233, vcc
	v_add_u32_e32 v3, 1, v6
	v_cmp_gt_u32_e32 vcc, 16, v3
	v_fmac_f32_e32 v234, 0x3e38aa3b, v49
	s_nop 0
	v_cndmask_b32_e32 v0, v0, v234, vcc
	v_add_u32_e32 v3, 2, v6
	v_cmp_gt_u32_e32 vcc, 16, v3
	v_mov_b32_e32 v3, 0xf149f2ca
	v_mov_b32_e32 v7, 0xf149f2ca
	v_fmac_f32_e32 v235, 0x3e38aa3b, v50
	s_nop 0
	v_cndmask_b32_e32 v7, v7, v235, vcc
	v_add_u32_e32 v8, 3, v6
	v_cmp_gt_u32_e32 vcc, 16, v8
	v_fmac_f32_e32 v236, 0x3e38aa3b, v51
	s_nop 0
	v_cndmask_b32_e32 v3, v3, v236, vcc
	v_add_u32_e32 v8, 8, v6
	v_cmp_gt_u32_e32 vcc, 16, v8
	v_mov_b32_e32 v8, 0xf149f2ca
	v_mov_b32_e32 v9, 0xf149f2ca
	v_fmac_f32_e32 v237, 0x3e38aa3b, v52
	s_nop 0
	v_cndmask_b32_e32 v9, v9, v237, vcc
	v_add_u32_e32 v10, 9, v6
	v_cmp_gt_u32_e32 vcc, 16, v10
	v_fmac_f32_e32 v238, 0x3e38aa3b, v53
	s_nop 0
	v_cndmask_b32_e32 v8, v8, v238, vcc
	v_add_u32_e32 v10, 10, v6
	v_cmp_gt_u32_e32 vcc, 16, v10
	v_mov_b32_e32 v10, 0xf149f2ca
	v_mov_b32_e32 v11, 0xf149f2ca
	v_fmac_f32_e32 v239, 0x3e38aa3b, v54
	s_nop 0
	v_cndmask_b32_e32 v11, v11, v239, vcc
	v_add_u32_e32 v12, 11, v6
	v_cmp_gt_u32_e32 vcc, 16, v12
	v_fmac_f32_e32 v240, 0x3e38aa3b, v55
	s_nop 0
	v_cndmask_b32_e32 v10, v10, v240, vcc
	v_cmp_lt_u32_e32 vcc, s52, v6
	v_mov_b32_e32 v13, 0xf149f2ca
	v_mov_b32_e32 v14, 0xf149f2ca
	v_fmac_f32_e32 v241, 0x3e38aa3b, v56
	s_nop 0
	v_cndmask_b32_e32 v14, v14, v241, vcc
	v_add_u32_e32 v12, 17, v6
	v_cmp_gt_u32_e32 vcc, 16, v12
	v_fmac_f32_e32 v242, 0x3e38aa3b, v57
	s_nop 0
	v_cndmask_b32_e32 v13, v13, v242, vcc
	v_add_u32_e32 v12, 18, v6
	v_cmp_gt_u32_e32 vcc, 16, v12
	v_mov_b32_e32 v12, 0xf149f2ca
	v_mov_b32_e32 v213, 0xf149f2ca
	v_fmac_f32_e32 v243, 0x3e38aa3b, v58
	s_nop 0
	v_cndmask_b32_e32 v213, v213, v243, vcc
	v_add_u32_e32 v15, 19, v6
	v_cmp_gt_u32_e32 vcc, 16, v15
	v_fmac_f32_e32 v244, 0x3e38aa3b, v59
	s_nop 0
	v_cndmask_b32_e32 v12, v12, v244, vcc
	v_add_u32_e32 v15, 24, v6
	v_cmp_gt_u32_e32 vcc, 16, v15
	v_mov_b32_e32 v15, 0xf149f2ca
	v_mov_b32_e32 v209, 0xf149f2ca
	v_fmac_f32_e32 v245, 0x3e38aa3b, v60
	s_nop 0
	v_cndmask_b32_e32 v209, v209, v245, vcc
	v_add_u32_e32 v48, 25, v6
	v_cmp_gt_u32_e32 vcc, 16, v48
	v_fmac_f32_e32 v246, 0x3e38aa3b, v61
	s_nop 0
	v_cndmask_b32_e32 v15, v15, v246, vcc
	v_add_u32_e32 v48, 26, v6
	v_cmp_gt_u32_e32 vcc, 16, v48
	v_mov_b32_e32 v226, 0xf149f2ca
	v_mov_b32_e32 v227, 0xf149f2ca
	v_fmac_f32_e32 v247, 0x3e38aa3b, v62
	s_nop 0
	v_cndmask_b32_e32 v227, v227, v247, vcc
	v_add_u32_e32 v6, 27, v6
	v_cmp_gt_u32_e32 vcc, 16, v6
	v_fmac_f32_e32 v248, 0x3e38aa3b, v63
	s_nop 0
	v_cndmask_b32_e32 v226, v226, v248, vcc
	v_max_f32_e32 v5, v0, v0
	v_max_f32_e32 v6, v1, v1
	v_max_f32_e32 v5, v6, v5
	v_max3_f32 v5, v5, v7, v3
	v_max3_f32 v5, v5, v9, v8
	v_max3_f32 v5, v5, v11, v10
	v_max3_f32 v5, v5, v14, v13
	v_max3_f32 v5, v5, v213, v12
	v_max3_f32 v5, v5, v209, v15
	v_max3_f32 v6, v5, v227, v226
	ds_bpermute_b32 v48, v224, v6
	v_mov_b64_e32 v[78:79], v[46:47]
	v_mov_b32_e32 v5, v201
	v_mov_b32_e32 v205, v4
	v_mov_b64_e32 v[76:77], v[44:45]
	s_waitcnt lgkmcnt(0)
	v_max3_f32 v6, v4, v6, v48
	v_mov_b64_e32 v[62:63], v[30:31]
	v_mov_b64_e32 v[74:75], v[42:43]
	v_mov_b64_e32 v[72:73], v[40:41]
	v_mov_b64_e32 v[70:71], v[38:39]
	v_mov_b64_e32 v[68:69], v[36:37]
	v_mov_b64_e32 v[66:67], v[34:35]
	v_mov_b64_e32 v[64:65], v[32:33]
	v_cmp_gt_f32_e32 vcc, v6, v4
	v_mov_b64_e32 v[60:61], v[28:29]
	v_mov_b64_e32 v[58:59], v[26:27]
	v_mov_b64_e32 v[56:57], v[24:25]
	v_mov_b64_e32 v[54:55], v[22:23]
	v_mov_b64_e32 v[52:53], v[20:21]
	v_mov_b64_e32 v[50:51], v[18:19]
	v_mov_b64_e32 v[48:49], v[16:17]
	s_cbranch_vccz .LBB0_910
	v_sub_f32_e32 v5, v4, v6
	v_exp_f32_e32 v64, v5
	v_mov_b32_e32 v205, v6
	v_mul_f32_e32 v5, v201, v64
	v_pk_mul_f32 v[62:63], v[30:31], v[64:65] op_sel_hi:[1,0]
	v_pk_mul_f32 v[60:61], v[28:29], v[64:65] op_sel_hi:[1,0]
	v_pk_mul_f32 v[58:59], v[26:27], v[64:65] op_sel_hi:[1,0]
	v_pk_mul_f32 v[56:57], v[24:25], v[64:65] op_sel_hi:[1,0]
	v_pk_mul_f32 v[54:55], v[22:23], v[64:65] op_sel_hi:[1,0]
	v_pk_mul_f32 v[52:53], v[20:21], v[64:65] op_sel_hi:[1,0]
	v_pk_mul_f32 v[50:51], v[18:19], v[64:65] op_sel_hi:[1,0]
	v_pk_mul_f32 v[48:49], v[16:17], v[64:65] op_sel_hi:[1,0]
	v_pk_mul_f32 v[78:79], v[46:47], v[64:65] op_sel_hi:[1,0]
	v_pk_mul_f32 v[76:77], v[44:45], v[64:65] op_sel_hi:[1,0]
	v_pk_mul_f32 v[74:75], v[42:43], v[64:65] op_sel_hi:[1,0]
	v_pk_mul_f32 v[72:73], v[40:41], v[64:65] op_sel_hi:[1,0]
	v_pk_mul_f32 v[70:71], v[38:39], v[64:65] op_sel_hi:[1,0]
	v_pk_mul_f32 v[68:69], v[36:37], v[64:65] op_sel_hi:[1,0]
	v_pk_mul_f32 v[66:67], v[34:35], v[64:65] op_sel_hi:[1,0]
	v_pk_mul_f32 v[64:65], v[32:33], v[64:65] op_sel_hi:[1,0]

.LBB0_914:
	s_cmp_gt_u32 s62, 14
	s_mov_b64 s[10:11], -1
	s_cbranch_scc0 .LBB0_983
	s_sub_i32 s10, s20, 19
	s_and_b32 s11, s10, 1
	s_lshr_b32 s10, s10, 1
	s_add_i32 s10, s10, s60
	v_lshl_or_b32 v0, s11, 5, v198
	s_mulk_i32 s10, 0x7c
	s_add_i32 s10, s15, s10
	v_sub_u32_e32 v1, v0, v193
	v_lshl_add_u32 v213, v1, 2, s10
	s_cmp_lg_u32 s11, s47
	v_sub_u32_e32 v226, v0, v223
	s_mov_b64 s[10:11], -1
	s_cbranch_scc0 .LBB0_940
	s_and_b64 vcc, exec, s[6:7]
	s_cbranch_vccz .LBB0_928
	s_waitcnt vmcnt(7)
	v_mfma_f32_32x32x16_bf16 v[4:19], v[124:127], v[80:83], 0
	v_add_u32_e32 v0, 24, v226
	v_cmp_gt_u32_e32 vcc, 16, v0
	v_mov_b32_e32 v0, 0xf149f2ca
	v_mov_b32_e32 v1, 0xf149f2ca
	s_waitcnt vmcnt(5)
	v_mfma_f32_32x32x16_bf16 v[4:19], v[136:139], v[84:87], v[4:19]
	s_waitcnt vmcnt(3)
	v_mfma_f32_32x32x16_bf16 v[4:19], v[144:147], v[88:91], v[4:19]
	s_waitcnt vmcnt(2)
	v_mfma_f32_32x32x16_bf16 v[4:19], v[148:151], v[92:95], v[4:19]
	ds_read_b32 v233, v213 offset:2048
	ds_read_b32 v234, v213 offset:2052
	ds_read_b32 v235, v213 offset:2056
	ds_read_b32 v236, v213 offset:2060
	s_waitcnt lgkmcnt(0)
	s_nop 7
	v_fmac_f32_e32 v233, 0x3e38aa3b, v16
	s_nop 0
	v_cndmask_b32_e32 v1, v1, v233, vcc
	v_add_u32_e32 v3, 25, v226
	v_cmp_gt_u32_e32 vcc, 16, v3
	v_fmac_f32_e32 v234, 0x3e38aa3b, v17
	s_nop 0
	v_cndmask_b32_e32 v0, v0, v234, vcc
	v_add_u32_e32 v3, 26, v226
	v_cmp_gt_u32_e32 vcc, 16, v3
	v_mov_b32_e32 v3, 0xf149f2ca
	s_nop 0
	v_mov_b32_e32 v5, 0xf149f2ca
	v_fmac_f32_e32 v235, 0x3e38aa3b, v18
	s_nop 0
	v_cndmask_b32_e32 v5, v5, v235, vcc
	v_add_u32_e32 v4, 27, v226
	v_cmp_gt_u32_e32 vcc, 16, v4
	v_fmac_f32_e32 v236, 0x3e38aa3b, v19
	s_nop 0
	v_cndmask_b32_e32 v3, v3, v236, vcc
	v_max_f32_e32 v4, v0, v0
	v_max_f32_e32 v6, v1, v1
	v_max_f32_e32 v4, v6, v4
	v_max3_f32 v7, v4, v5, v3
	ds_bpermute_b32 v8, v224, v7
	v_mov_b64_e32 v[32:33], v[64:65]
	v_mov_b64_e32 v[16:17], v[48:49]
	v_mov_b32_e32 v6, v209
	v_mov_b32_e32 v4, v205
	s_waitcnt lgkmcnt(0)
	v_max3_f32 v7, v205, v7, v8
	v_mov_b64_e32 v[34:35], v[66:67]
	v_mov_b64_e32 v[36:37], v[68:69]
	v_mov_b64_e32 v[38:39], v[70:71]
	v_mov_b64_e32 v[40:41], v[72:73]
	v_mov_b64_e32 v[42:43], v[74:75]
	v_mov_b64_e32 v[44:45], v[76:77]
	v_mov_b64_e32 v[46:47], v[78:79]
	v_cmp_gt_f32_e32 vcc, v7, v205
	v_mov_b64_e32 v[18:19], v[50:51]
	v_mov_b64_e32 v[20:21], v[52:53]
	v_mov_b64_e32 v[22:23], v[54:55]
	v_mov_b64_e32 v[24:25], v[56:57]
	v_mov_b64_e32 v[26:27], v[58:59]
	v_mov_b64_e32 v[28:29], v[60:61]
	v_mov_b64_e32 v[30:31], v[62:63]
	s_cbranch_vccz .LBB0_927
	v_sub_f32_e32 v4, v205, v7
	v_exp_f32_e32 v4, v4
	s_nop 0
	v_mul_f32_e32 v6, v209, v4
	v_pk_mul_f32 v[30:31], v[62:63], v[4:5] op_sel_hi:[1,0]
	v_pk_mul_f32 v[28:29], v[60:61], v[4:5] op_sel_hi:[1,0]
	v_pk_mul_f32 v[26:27], v[58:59], v[4:5] op_sel_hi:[1,0]
	v_pk_mul_f32 v[24:25], v[56:57], v[4:5] op_sel_hi:[1,0]
	v_pk_mul_f32 v[22:23], v[54:55], v[4:5] op_sel_hi:[1,0]
	v_pk_mul_f32 v[20:21], v[52:53], v[4:5] op_sel_hi:[1,0]
	v_pk_mul_f32 v[18:19], v[50:51], v[4:5] op_sel_hi:[1,0]
	v_pk_mul_f32 v[16:17], v[48:49], v[4:5] op_sel_hi:[1,0]
	v_pk_mul_f32 v[46:47], v[78:79], v[4:5] op_sel_hi:[1,0]
	v_pk_mul_f32 v[44:45], v[76:77], v[4:5] op_sel_hi:[1,0]
	v_pk_mul_f32 v[42:43], v[74:75], v[4:5] op_sel_hi:[1,0]
	v_pk_mul_f32 v[40:41], v[72:73], v[4:5] op_sel_hi:[1,0]
	v_pk_mul_f32 v[38:39], v[70:71], v[4:5] op_sel_hi:[1,0]
	v_pk_mul_f32 v[36:37], v[68:69], v[4:5] op_sel_hi:[1,0]
	v_pk_mul_f32 v[34:35], v[66:67], v[4:5] op_sel_hi:[1,0]
	v_pk_mul_f32 v[32:33], v[64:65], v[4:5] op_sel_hi:[1,0]
	v_mov_b32_e32 v4, v7

.LBB0_928:
	s_and_b64 vcc, exec, s[10:11]
	s_cbranch_vccz .LBB0_1055
	s_waitcnt vmcnt(7)
	v_mfma_f32_32x32x16_bf16 v[4:19], v[124:127], v[80:83], 0
	v_cmp_gt_u32_e32 vcc, 16, v226
	v_mov_b32_e32 v1, 0xf149f2ca
	v_mov_b32_e32 v0, 0xf149f2ca
	s_waitcnt vmcnt(5)
	v_mfma_f32_32x32x16_bf16 v[4:19], v[136:139], v[84:87], v[4:19]
	s_waitcnt vmcnt(3)
	v_mfma_f32_32x32x16_bf16 v[4:19], v[144:147], v[88:91], v[4:19]
	s_waitcnt vmcnt(2)
	v_mfma_f32_32x32x16_bf16 v[4:19], v[148:151], v[92:95], v[4:19]
	ds_read_b32 v233, v213 offset:1952
	ds_read_b32 v234, v213 offset:1956
	ds_read_b32 v235, v213 offset:1960
	ds_read_b32 v236, v213 offset:1964
	s_waitcnt lgkmcnt(0)
	s_nop 7
	v_fmac_f32_e32 v233, 0x3e38aa3b, v4
	s_nop 0
	v_cndmask_b32_e32 v0, v0, v233, vcc
	v_add_u32_e32 v3, 1, v226
	v_cmp_gt_u32_e32 vcc, 16, v3
	v_fmac_f32_e32 v234, 0x3e38aa3b, v5
	s_nop 0
	v_cndmask_b32_e32 v1, v1, v234, vcc
	v_add_u32_e32 v3, 2, v226
	v_cmp_gt_u32_e32 vcc, 16, v3
	s_nop 1
	v_mov_b32_e32 v5, 0xf149f2ca
	v_mov_b32_e32 v3, 0xf149f2ca
	v_fmac_f32_e32 v235, 0x3e38aa3b, v6
	s_nop 0
	v_cndmask_b32_e32 v3, v3, v235, vcc
	v_add_u32_e32 v4, 3, v226
	v_cmp_gt_u32_e32 vcc, 16, v4
	v_fmac_f32_e32 v236, 0x3e38aa3b, v7
	s_nop 0
	v_cndmask_b32_e32 v5, v5, v236, vcc
	v_max_f32_e32 v4, v1, v1
	v_max_f32_e32 v6, v0, v0
	v_max_f32_e32 v4, v6, v4
	v_max3_f32 v7, v4, v3, v5
	ds_bpermute_b32 v8, v224, v7
	v_mov_b64_e32 v[32:33], v[64:65]
	v_mov_b64_e32 v[16:17], v[48:49]
	v_mov_b32_e32 v6, v209
	v_mov_b32_e32 v4, v205
	s_waitcnt lgkmcnt(0)
	v_max3_f32 v7, v205, v7, v8
	v_mov_b64_e32 v[34:35], v[66:67]
	v_mov_b64_e32 v[36:37], v[68:69]
	v_mov_b64_e32 v[38:39], v[70:71]
	v_mov_b64_e32 v[40:41], v[72:73]
	v_mov_b64_e32 v[42:43], v[74:75]
	v_mov_b64_e32 v[44:45], v[76:77]
	v_mov_b64_e32 v[46:47], v[78:79]
	v_cmp_gt_f32_e32 vcc, v7, v205
	v_mov_b64_e32 v[18:19], v[50:51]
	v_mov_b64_e32 v[20:21], v[52:53]
	v_mov_b64_e32 v[22:23], v[54:55]
	v_mov_b64_e32 v[24:25], v[56:57]
	v_mov_b64_e32 v[26:27], v[58:59]
	v_mov_b64_e32 v[28:29], v[60:61]
	v_mov_b64_e32 v[30:31], v[62:63]
	s_cbranch_vccz .LBB0_939
	v_sub_f32_e32 v4, v205, v7
	v_exp_f32_e32 v4, v4
	s_nop 0
	v_mul_f32_e32 v6, v209, v4
	v_pk_mul_f32 v[30:31], v[62:63], v[4:5] op_sel_hi:[1,0]
	v_pk_mul_f32 v[28:29], v[60:61], v[4:5] op_sel_hi:[1,0]
	v_pk_mul_f32 v[26:27], v[58:59], v[4:5] op_sel_hi:[1,0]
	v_pk_mul_f32 v[24:25], v[56:57], v[4:5] op_sel_hi:[1,0]
	v_pk_mul_f32 v[22:23], v[54:55], v[4:5] op_sel_hi:[1,0]
	v_pk_mul_f32 v[20:21], v[52:53], v[4:5] op_sel_hi:[1,0]
	v_pk_mul_f32 v[18:19], v[50:51], v[4:5] op_sel_hi:[1,0]
	v_pk_mul_f32 v[16:17], v[48:49], v[4:5] op_sel_hi:[1,0]
	v_pk_mul_f32 v[46:47], v[78:79], v[4:5] op_sel_hi:[1,0]
	v_pk_mul_f32 v[44:45], v[76:77], v[4:5] op_sel_hi:[1,0]
	v_pk_mul_f32 v[42:43], v[74:75], v[4:5] op_sel_hi:[1,0]
	v_pk_mul_f32 v[40:41], v[72:73], v[4:5] op_sel_hi:[1,0]
	v_pk_mul_f32 v[38:39], v[70:71], v[4:5] op_sel_hi:[1,0]
	v_pk_mul_f32 v[36:37], v[68:69], v[4:5] op_sel_hi:[1,0]
	v_pk_mul_f32 v[34:35], v[66:67], v[4:5] op_sel_hi:[1,0]
	v_pk_mul_f32 v[32:33], v[64:65], v[4:5] op_sel_hi:[1,0]
	v_mov_b32_e32 v4, v7

.LBB0_941:
	s_waitcnt vmcnt(7)
	v_mfma_f32_32x32x16_bf16 v[4:19], v[124:127], v[80:83], 0
	v_cmp_gt_u32_e32 vcc, 16, v226
	v_mov_b32_e32 v0, 0xf149f2ca
	v_mov_b32_e32 v1, 0xf149f2ca
	s_waitcnt vmcnt(5)
	v_mfma_f32_32x32x16_bf16 v[4:19], v[136:139], v[84:87], v[4:19]
	s_waitcnt vmcnt(3)
	v_mfma_f32_32x32x16_bf16 v[4:19], v[144:147], v[88:91], v[4:19]
	s_waitcnt vmcnt(2)
	v_mfma_f32_32x32x16_bf16 v[4:19], v[148:151], v[92:95], v[4:19]
	ds_read_b32 v233, v213 offset:1952
	ds_read_b32 v234, v213 offset:1956
	ds_read_b32 v235, v213 offset:1960
	ds_read_b32 v236, v213 offset:1964
	ds_read_b32 v237, v213 offset:1984
	ds_read_b32 v238, v213 offset:1988
	ds_read_b32 v239, v213 offset:1992
	ds_read_b32 v240, v213 offset:1996
	ds_read_b32 v241, v213 offset:2016
	ds_read_b32 v242, v213 offset:2020
	ds_read_b32 v243, v213 offset:2024
	ds_read_b32 v244, v213 offset:2028
	ds_read_b32 v245, v213 offset:2048
	ds_read_b32 v246, v213 offset:2052
	ds_read_b32 v247, v213 offset:2056
	ds_read_b32 v248, v213 offset:2060
	s_waitcnt lgkmcnt(0)
	v_fmac_f32_e32 v233, 0x3e38aa3b, v4
	s_nop 0
	v_cndmask_b32_e32 v1, v1, v233, vcc
	v_add_u32_e32 v3, 1, v226
	v_cmp_gt_u32_e32 vcc, 16, v3
	v_fmac_f32_e32 v234, 0x3e38aa3b, v5
	s_nop 0
	v_cndmask_b32_e32 v0, v0, v234, vcc
	v_add_u32_e32 v3, 2, v226
	v_cmp_gt_u32_e32 vcc, 16, v3
	v_mov_b32_e32 v3, 0xf149f2ca
	s_nop 0
	v_mov_b32_e32 v5, 0xf149f2ca
	v_fmac_f32_e32 v235, 0x3e38aa3b, v6
	s_nop 0
	v_cndmask_b32_e32 v5, v5, v235, vcc
	v_add_u32_e32 v4, 3, v226
	v_cmp_gt_u32_e32 vcc, 16, v4
	v_fmac_f32_e32 v236, 0x3e38aa3b, v7
	s_nop 0
	v_cndmask_b32_e32 v3, v3, v236, vcc
	v_add_u32_e32 v4, 8, v226
	v_cmp_gt_u32_e32 vcc, 16, v4
	v_mov_b32_e32 v6, 0xf149f2ca
	v_mov_b32_e32 v7, 0xf149f2ca
	v_fmac_f32_e32 v237, 0x3e38aa3b, v8
	s_nop 0
	v_cndmask_b32_e32 v7, v7, v237, vcc
	v_add_u32_e32 v4, 9, v226
	v_cmp_gt_u32_e32 vcc, 16, v4
	v_fmac_f32_e32 v238, 0x3e38aa3b, v9
	s_nop 0
	v_cndmask_b32_e32 v6, v6, v238, vcc
	v_add_u32_e32 v4, 10, v226
	v_cmp_gt_u32_e32 vcc, 16, v4
	v_mov_b32_e32 v8, 0xf149f2ca
	v_mov_b32_e32 v9, 0xf149f2ca
	v_fmac_f32_e32 v239, 0x3e38aa3b, v10
	s_nop 0
	v_cndmask_b32_e32 v9, v9, v239, vcc
	v_add_u32_e32 v4, 11, v226
	v_cmp_gt_u32_e32 vcc, 16, v4
	v_fmac_f32_e32 v240, 0x3e38aa3b, v11
	s_nop 0
	v_cndmask_b32_e32 v8, v8, v240, vcc
	v_cmp_lt_u32_e32 vcc, s52, v226
	v_mov_b32_e32 v11, 0xf149f2ca
	v_mov_b32_e32 v201, 0xf149f2ca
	v_fmac_f32_e32 v241, 0x3e38aa3b, v12
	s_nop 0
	v_cndmask_b32_e32 v201, v201, v241, vcc
	v_add_u32_e32 v4, 17, v226
	v_cmp_gt_u32_e32 vcc, 16, v4
	v_fmac_f32_e32 v242, 0x3e38aa3b, v13
	s_nop 0
	v_cndmask_b32_e32 v11, v11, v242, vcc
	v_add_u32_e32 v4, 18, v226
	v_cmp_gt_u32_e32 vcc, 16, v4
	v_mov_b32_e32 v10, 0xf149f2ca
	v_mov_b32_e32 v227, 0xf149f2ca
	v_fmac_f32_e32 v243, 0x3e38aa3b, v14
	s_nop 0
	v_cndmask_b32_e32 v227, v227, v243, vcc
	v_add_u32_e32 v4, 19, v226
	v_cmp_gt_u32_e32 vcc, 16, v4
	v_fmac_f32_e32 v244, 0x3e38aa3b, v15
	s_nop 0
	v_cndmask_b32_e32 v10, v10, v244, vcc
	v_add_u32_e32 v4, 24, v226
	v_cmp_gt_u32_e32 vcc, 16, v4
	v_mov_b32_e32 v12, 0xf149f2ca
	v_mov_b32_e32 v13, 0xf149f2ca
	v_fmac_f32_e32 v245, 0x3e38aa3b, v16
	s_nop 0
	v_cndmask_b32_e32 v13, v13, v245, vcc
	v_add_u32_e32 v4, 25, v226
	v_cmp_gt_u32_e32 vcc, 16, v4
	v_fmac_f32_e32 v246, 0x3e38aa3b, v17
	s_nop 0
	v_cndmask_b32_e32 v12, v12, v246, vcc
	v_add_u32_e32 v4, 26, v226
	v_cmp_gt_u32_e32 vcc, 16, v4
	v_mov_b32_e32 v14, 0xf149f2ca
	v_mov_b32_e32 v15, 0xf149f2ca
	v_fmac_f32_e32 v247, 0x3e38aa3b, v18
	s_nop 0
	v_cndmask_b32_e32 v15, v15, v247, vcc
	v_add_u32_e32 v4, 27, v226
	v_cmp_gt_u32_e32 vcc, 16, v4
	v_fmac_f32_e32 v248, 0x3e38aa3b, v19
	s_nop 0
	v_cndmask_b32_e32 v14, v14, v248, vcc
	v_max_f32_e32 v4, v0, v0
	v_max_f32_e32 v16, v1, v1
	v_max_f32_e32 v4, v16, v4
	v_max3_f32 v4, v4, v5, v3
	v_max3_f32 v4, v4, v7, v6
	v_max3_f32 v4, v4, v9, v8
	v_max3_f32 v4, v4, v201, v11
	v_max3_f32 v4, v4, v227, v10
	v_max3_f32 v4, v4, v13, v12
	v_max3_f32 v16, v4, v15, v14
	ds_bpermute_b32 v17, v224, v16
	v_mov_b64_e32 v[32:33], v[64:65]
	v_mov_b32_e32 v213, v209
	v_mov_b32_e32 v4, v205
	v_mov_b64_e32 v[34:35], v[66:67]
	s_waitcnt lgkmcnt(0)
	v_max3_f32 v226, v205, v16, v17
	v_mov_b64_e32 v[16:17], v[48:49]
	v_mov_b64_e32 v[36:37], v[68:69]
	v_mov_b64_e32 v[38:39], v[70:71]
	v_mov_b64_e32 v[40:41], v[72:73]
	v_mov_b64_e32 v[42:43], v[74:75]
	v_mov_b64_e32 v[44:45], v[76:77]
	v_mov_b64_e32 v[46:47], v[78:79]
	v_cmp_gt_f32_e32 vcc, v226, v205
	v_mov_b64_e32 v[18:19], v[50:51]
	v_mov_b64_e32 v[20:21], v[52:53]
	v_mov_b64_e32 v[22:23], v[54:55]
	v_mov_b64_e32 v[24:25], v[56:57]
	v_mov_b64_e32 v[26:27], v[58:59]
	v_mov_b64_e32 v[28:29], v[60:61]
	v_mov_b64_e32 v[30:31], v[62:63]
	s_cbranch_vccz .LBB0_975
	v_sub_f32_e32 v4, v205, v226
	v_exp_f32_e32 v4, v4
	s_nop 0
	v_mul_f32_e32 v213, v209, v4
	v_pk_mul_f32 v[30:31], v[62:63], v[4:5] op_sel_hi:[1,0]
	v_pk_mul_f32 v[28:29], v[60:61], v[4:5] op_sel_hi:[1,0]
	v_pk_mul_f32 v[26:27], v[58:59], v[4:5] op_sel_hi:[1,0]
	v_pk_mul_f32 v[24:25], v[56:57], v[4:5] op_sel_hi:[1,0]
	v_pk_mul_f32 v[22:23], v[54:55], v[4:5] op_sel_hi:[1,0]
	v_pk_mul_f32 v[20:21], v[52:53], v[4:5] op_sel_hi:[1,0]
	v_pk_mul_f32 v[18:19], v[50:51], v[4:5] op_sel_hi:[1,0]
	v_pk_mul_f32 v[16:17], v[48:49], v[4:5] op_sel_hi:[1,0]
	v_pk_mul_f32 v[46:47], v[78:79], v[4:5] op_sel_hi:[1,0]
	v_pk_mul_f32 v[44:45], v[76:77], v[4:5] op_sel_hi:[1,0]
	v_pk_mul_f32 v[42:43], v[74:75], v[4:5] op_sel_hi:[1,0]
	v_pk_mul_f32 v[40:41], v[72:73], v[4:5] op_sel_hi:[1,0]
	v_pk_mul_f32 v[38:39], v[70:71], v[4:5] op_sel_hi:[1,0]
	v_pk_mul_f32 v[36:37], v[68:69], v[4:5] op_sel_hi:[1,0]
	v_pk_mul_f32 v[34:35], v[66:67], v[4:5] op_sel_hi:[1,0]
	v_pk_mul_f32 v[32:33], v[64:65], v[4:5] op_sel_hi:[1,0]
	v_mov_b32_e32 v4, v226

.LBB0_988:
	s_cmp_gt_u32 s62, 13
	s_mov_b64 s[10:11], -1
	s_cbranch_scc0 .LBB0_1051
	s_sub_i32 s10, s20, 18
	s_lshr_b32 s10, s10, 1
	s_and_b32 s11, s62, 1
	s_add_i32 s10, s10, s60
	v_lshl_or_b32 v0, s11, 5, v198
	s_mulk_i32 s10, 0x7c
	s_add_i32 s10, s15, s10
	v_sub_u32_e32 v1, v0, v193
	v_lshl_add_u32 v5, v1, 2, s10
	s_cmp_lg_u32 s11, s47
	v_sub_u32_e32 v6, v0, v223
	s_mov_b64 s[10:11], -1
	s_cbranch_scc0 .LBB0_1014
	s_and_b64 vcc, exec, s[6:7]
	s_cbranch_vccz .LBB0_1002
	s_waitcnt vmcnt(7)
	v_mfma_f32_32x32x16_bf16 v[48:63], v[160:163], v[80:83], 0
	v_add_u32_e32 v0, 24, v6
	v_cmp_gt_u32_e32 vcc, 16, v0
	v_mov_b32_e32 v0, 0xf149f2ca
	v_mov_b32_e32 v1, 0xf149f2ca
	s_waitcnt vmcnt(6)
	v_mfma_f32_32x32x16_bf16 v[48:63], v[164:167], v[84:87], v[48:63]
	s_waitcnt vmcnt(3)
	v_mfma_f32_32x32x16_bf16 v[48:63], v[168:171], v[88:91], v[48:63]
	s_waitcnt vmcnt(2)
	v_mfma_f32_32x32x16_bf16 v[48:63], v[180:183], v[92:95], v[48:63]
	ds_read_b32 v233, v5 offset:2048
	ds_read_b32 v234, v5 offset:2052
	ds_read_b32 v235, v5 offset:2056
	ds_read_b32 v236, v5 offset:2060
	s_waitcnt lgkmcnt(0)
	s_nop 7
	v_fmac_f32_e32 v233, 0x3e38aa3b, v60
	s_nop 0
	v_cndmask_b32_e32 v1, v1, v233, vcc
	v_add_u32_e32 v3, 25, v6
	v_cmp_gt_u32_e32 vcc, 16, v3
	v_fmac_f32_e32 v234, 0x3e38aa3b, v61
	s_nop 0
	v_cndmask_b32_e32 v0, v0, v234, vcc
	v_add_u32_e32 v3, 26, v6
	v_cmp_gt_u32_e32 vcc, 16, v3
	v_mov_b32_e32 v3, 0xf149f2ca
	v_mov_b32_e32 v7, 0xf149f2ca
	v_fmac_f32_e32 v235, 0x3e38aa3b, v62
	s_nop 0
	v_cndmask_b32_e32 v7, v7, v235, vcc
	v_add_u32_e32 v8, 27, v6
	v_cmp_gt_u32_e32 vcc, 16, v8
	v_fmac_f32_e32 v236, 0x3e38aa3b, v63
	s_nop 0
	v_cndmask_b32_e32 v3, v3, v236, vcc
	v_max_f32_e32 v8, v0, v0
	v_max_f32_e32 v9, v1, v1
	v_max_f32_e32 v8, v9, v8
	v_max3_f32 v9, v8, v7, v3
	ds_bpermute_b32 v11, v224, v9
	v_mov_b64_e32 v[78:79], v[46:47]
	v_mov_b64_e32 v[62:63], v[30:31]
	v_mov_b32_e32 v8, v201
	v_mov_b32_e32 v10, v4
	s_waitcnt lgkmcnt(0)
	v_max3_f32 v9, v4, v9, v11
	v_mov_b64_e32 v[76:77], v[44:45]
	v_mov_b64_e32 v[74:75], v[42:43]
	v_mov_b64_e32 v[72:73], v[40:41]
	v_mov_b64_e32 v[70:71], v[38:39]
	v_mov_b64_e32 v[68:69], v[36:37]
	v_mov_b64_e32 v[66:67], v[34:35]
	v_mov_b64_e32 v[64:65], v[32:33]
	v_cmp_gt_f32_e32 vcc, v9, v4
	v_mov_b64_e32 v[60:61], v[28:29]
	v_mov_b64_e32 v[58:59], v[26:27]
	v_mov_b64_e32 v[56:57], v[24:25]
	v_mov_b64_e32 v[54:55], v[22:23]
	v_mov_b64_e32 v[52:53], v[20:21]
	v_mov_b64_e32 v[50:51], v[18:19]
	v_mov_b64_e32 v[48:49], v[16:17]
	s_cbranch_vccz .LBB0_1001
	v_sub_f32_e32 v8, v4, v9
	v_exp_f32_e32 v10, v8
	s_nop 0
	v_mul_f32_e32 v8, v201, v10
	v_pk_mul_f32 v[62:63], v[30:31], v[10:11] op_sel_hi:[1,0]
	v_pk_mul_f32 v[60:61], v[28:29], v[10:11] op_sel_hi:[1,0]
	v_pk_mul_f32 v[58:59], v[26:27], v[10:11] op_sel_hi:[1,0]
	v_pk_mul_f32 v[56:57], v[24:25], v[10:11] op_sel_hi:[1,0]
	v_pk_mul_f32 v[54:55], v[22:23], v[10:11] op_sel_hi:[1,0]
	v_pk_mul_f32 v[52:53], v[20:21], v[10:11] op_sel_hi:[1,0]
	v_pk_mul_f32 v[50:51], v[18:19], v[10:11] op_sel_hi:[1,0]
	v_pk_mul_f32 v[48:49], v[16:17], v[10:11] op_sel_hi:[1,0]
	v_pk_mul_f32 v[78:79], v[46:47], v[10:11] op_sel_hi:[1,0]
	v_pk_mul_f32 v[76:77], v[44:45], v[10:11] op_sel_hi:[1,0]
	v_pk_mul_f32 v[74:75], v[42:43], v[10:11] op_sel_hi:[1,0]
	v_pk_mul_f32 v[72:73], v[40:41], v[10:11] op_sel_hi:[1,0]
	v_pk_mul_f32 v[70:71], v[38:39], v[10:11] op_sel_hi:[1,0]
	v_pk_mul_f32 v[68:69], v[36:37], v[10:11] op_sel_hi:[1,0]
	v_pk_mul_f32 v[66:67], v[34:35], v[10:11] op_sel_hi:[1,0]
	v_pk_mul_f32 v[64:65], v[32:33], v[10:11] op_sel_hi:[1,0]
	v_mov_b32_e32 v10, v9

.LBB0_1002:
	s_and_b64 vcc, exec, s[10:11]
	s_cbranch_vccz .LBB0_1056
	s_waitcnt vmcnt(7)
	v_mfma_f32_32x32x16_bf16 v[48:63], v[160:163], v[80:83], 0
	v_cmp_gt_u32_e32 vcc, 16, v6
	v_mov_b32_e32 v1, 0xf149f2ca
	v_mov_b32_e32 v0, 0xf149f2ca
	s_waitcnt vmcnt(6)
	v_mfma_f32_32x32x16_bf16 v[48:63], v[164:167], v[84:87], v[48:63]
	s_waitcnt vmcnt(3)
	v_mfma_f32_32x32x16_bf16 v[48:63], v[168:171], v[88:91], v[48:63]
	s_waitcnt vmcnt(2)
	v_mfma_f32_32x32x16_bf16 v[48:63], v[180:183], v[92:95], v[48:63]
	ds_read_b32 v233, v5 offset:1952
	ds_read_b32 v234, v5 offset:1956
	ds_read_b32 v235, v5 offset:1960
	ds_read_b32 v236, v5 offset:1964
	s_waitcnt lgkmcnt(0)
	s_nop 7
	v_fmac_f32_e32 v233, 0x3e38aa3b, v48
	s_nop 0
	v_cndmask_b32_e32 v0, v0, v233, vcc
	v_add_u32_e32 v3, 1, v6
	v_cmp_gt_u32_e32 vcc, 16, v3
	v_fmac_f32_e32 v234, 0x3e38aa3b, v49
	s_nop 0
	v_cndmask_b32_e32 v1, v1, v234, vcc
	v_add_u32_e32 v3, 2, v6
	v_cmp_gt_u32_e32 vcc, 16, v3
	v_mov_b32_e32 v7, 0xf149f2ca
	v_mov_b32_e32 v3, 0xf149f2ca
	v_fmac_f32_e32 v235, 0x3e38aa3b, v50
	s_nop 0
	v_cndmask_b32_e32 v3, v3, v235, vcc
	v_add_u32_e32 v8, 3, v6
	v_cmp_gt_u32_e32 vcc, 16, v8
	v_fmac_f32_e32 v236, 0x3e38aa3b, v51
	s_nop 0
	v_cndmask_b32_e32 v7, v7, v236, vcc
	v_max_f32_e32 v8, v1, v1
	v_max_f32_e32 v9, v0, v0
	v_max_f32_e32 v8, v9, v8
	v_max3_f32 v9, v8, v3, v7
	ds_bpermute_b32 v11, v224, v9
	v_mov_b64_e32 v[78:79], v[46:47]
	v_mov_b64_e32 v[62:63], v[30:31]
	v_mov_b32_e32 v8, v201
	v_mov_b32_e32 v10, v4
	s_waitcnt lgkmcnt(0)
	v_max3_f32 v9, v4, v9, v11
	v_mov_b64_e32 v[76:77], v[44:45]
	v_mov_b64_e32 v[74:75], v[42:43]
	v_mov_b64_e32 v[72:73], v[40:41]
	v_mov_b64_e32 v[70:71], v[38:39]
	v_mov_b64_e32 v[68:69], v[36:37]
	v_mov_b64_e32 v[66:67], v[34:35]
	v_mov_b64_e32 v[64:65], v[32:33]
	v_cmp_gt_f32_e32 vcc, v9, v4
	v_mov_b64_e32 v[60:61], v[28:29]
	v_mov_b64_e32 v[58:59], v[26:27]
	v_mov_b64_e32 v[56:57], v[24:25]
	v_mov_b64_e32 v[54:55], v[22:23]
	v_mov_b64_e32 v[52:53], v[20:21]
	v_mov_b64_e32 v[50:51], v[18:19]
	v_mov_b64_e32 v[48:49], v[16:17]
	s_cbranch_vccz .LBB0_1013
	v_sub_f32_e32 v8, v4, v9
	v_exp_f32_e32 v10, v8
	s_nop 0
	v_mul_f32_e32 v8, v201, v10
	v_pk_mul_f32 v[62:63], v[30:31], v[10:11] op_sel_hi:[1,0]
	v_pk_mul_f32 v[60:61], v[28:29], v[10:11] op_sel_hi:[1,0]
	v_pk_mul_f32 v[58:59], v[26:27], v[10:11] op_sel_hi:[1,0]
	v_pk_mul_f32 v[56:57], v[24:25], v[10:11] op_sel_hi:[1,0]
	v_pk_mul_f32 v[54:55], v[22:23], v[10:11] op_sel_hi:[1,0]
	v_pk_mul_f32 v[52:53], v[20:21], v[10:11] op_sel_hi:[1,0]
	v_pk_mul_f32 v[50:51], v[18:19], v[10:11] op_sel_hi:[1,0]
	v_pk_mul_f32 v[48:49], v[16:17], v[10:11] op_sel_hi:[1,0]
	v_pk_mul_f32 v[78:79], v[46:47], v[10:11] op_sel_hi:[1,0]
	v_pk_mul_f32 v[76:77], v[44:45], v[10:11] op_sel_hi:[1,0]
	v_pk_mul_f32 v[74:75], v[42:43], v[10:11] op_sel_hi:[1,0]
	v_pk_mul_f32 v[72:73], v[40:41], v[10:11] op_sel_hi:[1,0]
	v_pk_mul_f32 v[70:71], v[38:39], v[10:11] op_sel_hi:[1,0]
	v_pk_mul_f32 v[68:69], v[36:37], v[10:11] op_sel_hi:[1,0]
	v_pk_mul_f32 v[66:67], v[34:35], v[10:11] op_sel_hi:[1,0]
	v_pk_mul_f32 v[64:65], v[32:33], v[10:11] op_sel_hi:[1,0]
	v_mov_b32_e32 v10, v9

.LBB0_1015:
	s_waitcnt vmcnt(7)
	v_mfma_f32_32x32x16_bf16 v[48:63], v[160:163], v[80:83], 0
	v_cmp_gt_u32_e32 vcc, 16, v6
	v_mov_b32_e32 v0, 0xf149f2ca
	v_mov_b32_e32 v1, 0xf149f2ca
	s_waitcnt vmcnt(6)
	v_mfma_f32_32x32x16_bf16 v[48:63], v[164:167], v[84:87], v[48:63]
	s_waitcnt vmcnt(3)
	v_mfma_f32_32x32x16_bf16 v[48:63], v[168:171], v[88:91], v[48:63]
	s_waitcnt vmcnt(2)
	v_mfma_f32_32x32x16_bf16 v[48:63], v[180:183], v[92:95], v[48:63]
	ds_read_b32 v233, v5 offset:1952
	ds_read_b32 v234, v5 offset:1956
	ds_read_b32 v235, v5 offset:1960
	ds_read_b32 v236, v5 offset:1964
	ds_read_b32 v237, v5 offset:1984
	ds_read_b32 v238, v5 offset:1988
	ds_read_b32 v239, v5 offset:1992
	ds_read_b32 v240, v5 offset:1996
	ds_read_b32 v241, v5 offset:2016
	ds_read_b32 v242, v5 offset:2020
	ds_read_b32 v243, v5 offset:2024
	ds_read_b32 v244, v5 offset:2028
	ds_read_b32 v245, v5 offset:2048
	ds_read_b32 v246, v5 offset:2052
	ds_read_b32 v247, v5 offset:2056
	ds_read_b32 v248, v5 offset:2060
	s_waitcnt lgkmcnt(0)
	v_fmac_f32_e32 v233, 0x3e38aa3b, v48
	s_nop 0
	v_cndmask_b32_e32 v1, v1, v233, vcc
	v_add_u32_e32 v3, 1, v6
	v_cmp_gt_u32_e32 vcc, 16, v3
	v_fmac_f32_e32 v234, 0x3e38aa3b, v49
	s_nop 0
	v_cndmask_b32_e32 v0, v0, v234, vcc
	v_add_u32_e32 v3, 2, v6
	v_cmp_gt_u32_e32 vcc, 16, v3
	v_mov_b32_e32 v3, 0xf149f2ca
	v_mov_b32_e32 v7, 0xf149f2ca
	v_fmac_f32_e32 v235, 0x3e38aa3b, v50
	s_nop 0
	v_cndmask_b32_e32 v7, v7, v235, vcc
	v_add_u32_e32 v8, 3, v6
	v_cmp_gt_u32_e32 vcc, 16, v8
	v_fmac_f32_e32 v236, 0x3e38aa3b, v51
	s_nop 0
	v_cndmask_b32_e32 v3, v3, v236, vcc
	v_add_u32_e32 v8, 8, v6
	v_cmp_gt_u32_e32 vcc, 16, v8
	v_mov_b32_e32 v8, 0xf149f2ca
	v_mov_b32_e32 v9, 0xf149f2ca
	v_fmac_f32_e32 v237, 0x3e38aa3b, v52
	s_nop 0
	v_cndmask_b32_e32 v9, v9, v237, vcc
	v_add_u32_e32 v10, 9, v6
	v_cmp_gt_u32_e32 vcc, 16, v10
	v_fmac_f32_e32 v238, 0x3e38aa3b, v53
	s_nop 0
	v_cndmask_b32_e32 v8, v8, v238, vcc
	v_add_u32_e32 v10, 10, v6
	v_cmp_gt_u32_e32 vcc, 16, v10
	v_mov_b32_e32 v11, 0xf149f2ca
	v_mov_b32_e32 v12, 0xf149f2ca
	v_fmac_f32_e32 v239, 0x3e38aa3b, v54
	s_nop 0
	v_cndmask_b32_e32 v12, v12, v239, vcc
	v_add_u32_e32 v10, 11, v6
	v_cmp_gt_u32_e32 vcc, 16, v10
	v_fmac_f32_e32 v240, 0x3e38aa3b, v55
	s_nop 0
	v_cndmask_b32_e32 v11, v11, v240, vcc
	v_cmp_lt_u32_e32 vcc, s52, v6
	v_mov_b32_e32 v14, 0xf149f2ca
	v_mov_b32_e32 v15, 0xf149f2ca
	v_fmac_f32_e32 v241, 0x3e38aa3b, v56
	s_nop 0
	v_cndmask_b32_e32 v15, v15, v241, vcc
	v_add_u32_e32 v10, 17, v6
	v_cmp_gt_u32_e32 vcc, 16, v10
	v_fmac_f32_e32 v242, 0x3e38aa3b, v57
	s_nop 0
	v_cndmask_b32_e32 v14, v14, v242, vcc
	v_add_u32_e32 v10, 18, v6
	v_cmp_gt_u32_e32 vcc, 16, v10
	v_mov_b32_e32 v13, 0xf149f2ca
	v_mov_b32_e32 v213, 0xf149f2ca
	v_fmac_f32_e32 v243, 0x3e38aa3b, v58
	s_nop 0
	v_cndmask_b32_e32 v213, v213, v243, vcc
	v_add_u32_e32 v10, 19, v6
	v_cmp_gt_u32_e32 vcc, 16, v10
	v_fmac_f32_e32 v244, 0x3e38aa3b, v59
	s_nop 0
	v_cndmask_b32_e32 v13, v13, v244, vcc
	v_add_u32_e32 v10, 24, v6
	v_cmp_gt_u32_e32 vcc, 16, v10
	v_mov_b32_e32 v205, 0xf149f2ca
	v_mov_b32_e32 v209, 0xf149f2ca
	v_fmac_f32_e32 v245, 0x3e38aa3b, v60
	s_nop 0
	v_cndmask_b32_e32 v209, v209, v245, vcc
	v_add_u32_e32 v10, 25, v6
	v_cmp_gt_u32_e32 vcc, 16, v10
	v_fmac_f32_e32 v246, 0x3e38aa3b, v61
	s_nop 0
	v_cndmask_b32_e32 v205, v205, v246, vcc
	v_add_u32_e32 v10, 26, v6
	v_cmp_gt_u32_e32 vcc, 16, v10
	v_mov_b32_e32 v226, 0xf149f2ca
	v_mov_b32_e32 v227, 0xf149f2ca
	v_fmac_f32_e32 v247, 0x3e38aa3b, v62
	s_nop 0
	v_cndmask_b32_e32 v227, v227, v247, vcc
	v_add_u32_e32 v6, 27, v6
	v_cmp_gt_u32_e32 vcc, 16, v6
	v_fmac_f32_e32 v248, 0x3e38aa3b, v63
	s_nop 0
	v_cndmask_b32_e32 v226, v226, v248, vcc
	v_max_f32_e32 v5, v0, v0
	v_max_f32_e32 v6, v1, v1
	v_max_f32_e32 v5, v6, v5
	v_max3_f32 v5, v5, v7, v3
	v_max3_f32 v5, v5, v9, v8
	v_max3_f32 v5, v5, v12, v11
	v_max3_f32 v5, v5, v15, v14
	v_max3_f32 v5, v5, v213, v13
	v_max3_f32 v5, v5, v209, v205
	v_max3_f32 v6, v5, v227, v226
	ds_bpermute_b32 v48, v224, v6
	v_mov_b64_e32 v[78:79], v[46:47]
	v_mov_b32_e32 v5, v201
	v_mov_b32_e32 v10, v4
	v_mov_b64_e32 v[76:77], v[44:45]
	s_waitcnt lgkmcnt(0)
	v_max3_f32 v6, v4, v6, v48
	v_mov_b64_e32 v[62:63], v[30:31]
	v_mov_b64_e32 v[74:75], v[42:43]
	v_mov_b64_e32 v[72:73], v[40:41]
	v_mov_b64_e32 v[70:71], v[38:39]
	v_mov_b64_e32 v[68:69], v[36:37]
	v_mov_b64_e32 v[66:67], v[34:35]
	v_mov_b64_e32 v[64:65], v[32:33]
	v_cmp_gt_f32_e32 vcc, v6, v4
	v_mov_b64_e32 v[60:61], v[28:29]
	v_mov_b64_e32 v[58:59], v[26:27]
	v_mov_b64_e32 v[56:57], v[24:25]
	v_mov_b64_e32 v[54:55], v[22:23]
	v_mov_b64_e32 v[52:53], v[20:21]
	v_mov_b64_e32 v[50:51], v[18:19]
	v_mov_b64_e32 v[48:49], v[16:17]
	s_cbranch_vccz .LBB0_1049
	v_sub_f32_e32 v5, v4, v6
	v_exp_f32_e32 v10, v5
	s_nop 0
	v_mul_f32_e32 v5, v201, v10
	v_pk_mul_f32 v[62:63], v[30:31], v[10:11] op_sel_hi:[1,0]
	v_pk_mul_f32 v[60:61], v[28:29], v[10:11] op_sel_hi:[1,0]
	v_pk_mul_f32 v[58:59], v[26:27], v[10:11] op_sel_hi:[1,0]
	v_pk_mul_f32 v[56:57], v[24:25], v[10:11] op_sel_hi:[1,0]
	v_pk_mul_f32 v[54:55], v[22:23], v[10:11] op_sel_hi:[1,0]
	v_pk_mul_f32 v[52:53], v[20:21], v[10:11] op_sel_hi:[1,0]
	v_pk_mul_f32 v[50:51], v[18:19], v[10:11] op_sel_hi:[1,0]
	v_pk_mul_f32 v[48:49], v[16:17], v[10:11] op_sel_hi:[1,0]
	v_pk_mul_f32 v[78:79], v[46:47], v[10:11] op_sel_hi:[1,0]
	v_pk_mul_f32 v[76:77], v[44:45], v[10:11] op_sel_hi:[1,0]
	v_pk_mul_f32 v[74:75], v[42:43], v[10:11] op_sel_hi:[1,0]
	v_pk_mul_f32 v[72:73], v[40:41], v[10:11] op_sel_hi:[1,0]
	v_pk_mul_f32 v[70:71], v[38:39], v[10:11] op_sel_hi:[1,0]
	v_pk_mul_f32 v[68:69], v[36:37], v[10:11] op_sel_hi:[1,0]
	v_pk_mul_f32 v[66:67], v[34:35], v[10:11] op_sel_hi:[1,0]
	v_pk_mul_f32 v[64:65], v[32:33], v[10:11] op_sel_hi:[1,0]
	v_mov_b32_e32 v10, v6
